# weight conversion of dif_qkv/dif_out/ret_qkvg/swa_out moved from P0 into idle workgroups at the tail of the lru_in GEMM phase
# speedup vs baseline: 1.0125x; 1.0053x over previous
; #define LAS __attribute__((address_space(3)))
; __device__ __forceinline__ float siluf(float x) { return x * sigmoidf(x); }
; #define REPLOOP(k) _Pragma("unroll 1") for (int rep_ = 0, nrep_ = (phase_group(k) == DUP_GROUP ? 2 : 1); rep_ < nrep_; ++rep_)
; #define INP(k) input_ptr(args, (k))
; __global__ void __launch_bounds__(NTHR, 2) fwd(Args args) {
;     ...
;     const int lo = args.ph_lo, hi = args.ph_hi;
;     ...
;     if (IN(0)) { REPLOOP(0) { PH_BEGIN();
;         LAS float* sl = (LAS float*)(lds + 81920);
;         for (int i = tid; i < 5 * D; i += NTHR) { const int r = i >> 11, k = i & (D - 1); const float v = r < 4 ? INP(I_C)[r * D + k] : INP(I_CCTX)[k]; sl[i] = siluf(v); }
.LBB0_11:
	s_or_b64 exec, exec, s[2:3]
	s_mov_b32 s2, 0
	v_writelane_b32 v255, s2, 63
	s_load_dwordx2 s[90:91], s[0:1], 0xe0
	s_waitcnt lgkmcnt(0)
	s_cmp_lt_i32 s90, 1
	s_cselect_b64 s[2:3], -1, 0
	s_cmp_gt_i32 s91, 0
	s_cselect_b64 s[4:5], -1, 0
	s_and_b64 s[2:3], s[2:3], s[4:5]
	s_andn2_b64 vcc, exec, s[2:3]
	s_cbranch_vccnz .LBB0_121
	v_mov_b32_e32 v0, 27
	s_add_u32 s2, s0, 0xe8
	s_load_dword s20, s[0:1], 0xe8
	s_addc_u32 s3, s1, 0
	v_readfirstlane_b32 s4, v0
	s_ashr_i32 s5, s4, 31
	s_lshl_b64 s[4:5], s[4:5], 3
	s_add_u32 s4, s0, s4
	s_addc_u32 s5, s1, s5
	s_load_dwordx2 s[4:5], s[4:5], 0x0
	s_and_b32 s6, s85, 0xffffffc0
	v_mbcnt_lo_u32_b32 v8, -1, 0
	v_mbcnt_hi_u32_b32 v8, -1, v8
	v_mov_b32_e32 v1, s96
	v_or_b32_e32 v0, s6, v8
	s_waitcnt lgkmcnt(0)
	v_mov_b32_e32 v2, s20
	s_movk_i32 s6, 0x2800
	v_readfirstlane_b32 s16, v0
	v_readfirstlane_b32 s15, v1
	v_readfirstlane_b32 s14, v2
	v_cmp_gt_i32_e32 vcc, s6, v0
	s_and_saveexec_b64 s[6:7], vcc
	s_cbranch_execz .LBB0_19
	v_ashrrev_i32_e32 v1, 31, v0
	v_lshlrev_b64 v[2:3], 2, v[0:1]
	v_lshl_add_u32 v1, v0, 2, 0
	v_add_u32_e32 v1, 0x14000, v1
	s_mov_b64 s[8:9], 0
	s_movk_i32 s17, 0x1fff
	v_mov_b32_e32 v5, 0
	s_mov_b64 s[10:11], 0x800
	s_movk_i32 s18, 0x25ff
	s_branch .LBB0_15

; #define LAS __attribute__((address_space(3)))
; #define INP(k) input_ptr(args, (k))
; __device__ __forceinline__ void tr_job(const float* W, int K, int N, bf16_t* WT, LAS float* scr, int lane, int gw, int NGW, int& base) {
;     const int nblk = N / 32, nitems = (K / 64) * nblk;
;     int it = ((gw - base) % NGW + NGW) % NGW; f32x4 v[8];
;     if (it < nitems) tr_load(W, N, 64 * (it / nblk), 32 * (it % nblk), lane, v);
; #pragma unroll 1
;     while (it < nitems) {
;         tr_put(scr, lane, v);
;         const int nit = it + NGW;
;         if (nit < nitems) tr_load(W, N, 64 * (nit / nblk), 32 * (nit % nblk), lane, v);
;         tr_out(WT, K, 64 * (it / nblk), 32 * (it % nblk), scr, lane);
; __global__ void __launch_bounds__(NTHR, 2) fwd(Args args) {
;     ...
;         tr_job(INP(I_LIN), D, 4096, (bf16_t*)(ws + W_LRU_IN), scr, lane, gw, NGW, base);
.LBB0_24:
	s_abs_i32 s9, s10
	v_cvt_f32_u32_e32 v0, s9
	s_mulk_i32 s12, 0x2100
	s_add_i32 s8, s12, 0
	s_sub_i32 s12, 0, s9
	v_rcp_iflag_f32_e32 v0, v0
	s_abs_i32 s13, s11
	s_ashr_i32 s7, s11, 31
	v_mov_b32_e32 v1, 10
	v_mul_f32_e32 v0, 0x4f7ffffe, v0
	v_cvt_u32_f32_e32 v0, v0
	v_lshrrev_b32_e32 v36, 3, v38
	v_readfirstlane_b32 s6, v1
	v_readfirstlane_b32 s15, v0
	s_mul_i32 s12, s12, s15
	s_mul_hi_u32 s12, s15, s12
	s_add_i32 s12, s15, s12
	s_mul_hi_u32 s15, s13, s12
	s_mul_i32 s15, s15, s9
	s_sub_i32 s13, s13, s15
	s_sub_i32 s15, s13, s9
	s_cmp_ge_u32 s13, s9
	s_cselect_b32 s13, s15, s13
	s_sub_i32 s15, s13, s9
	s_cmp_ge_u32 s13, s9
	s_cselect_b32 s13, s15, s13
	s_xor_b32 s13, s13, s7
	s_sub_i32 s7, s13, s7
	s_add_i32 s7, s7, s10
	s_ashr_i32 s13, s7, 31
	s_abs_i32 s7, s7
	s_mul_hi_u32 s15, s7, s12
	s_mul_i32 s15, s15, s9
	s_sub_i32 s7, s7, s15
	s_sub_i32 s15, s7, s9
	s_cmp_ge_u32 s7, s9
	s_cselect_b32 s7, s15, s7
	s_sub_i32 s15, s7, s9
	s_cmp_ge_u32 s7, s9
	s_cselect_b32 s7, s15, s7
	s_xor_b32 s7, s7, s13
	s_sub_i32 s13, s7, s13
	s_cmpk_gt_i32 s13, 0xfff
	v_lshlrev_b32_e32 v39, 4, v38
	v_lshlrev_b32_e32 v37, 3, v38
	s_cbranch_scc1 .LBB0_29
	v_readlane_b32 s98, v255, 63
	s_nop 0
	s_cmp_eq_u32 s98, 1
	s_cbranch_scc1 .LBB0_29
	s_ashr_i32 s7, s6, 31
	s_lshl_b64 s[6:7], s[6:7], 3
	s_add_u32 s6, s0, s6
	s_addc_u32 s7, s1, s7
	s_ashr_i32 s15, s13, 31
	s_lshr_b32 s15, s15, 25
	s_add_i32 s15, s13, s15
	s_load_dwordx2 s[6:7], s[6:7], 0x0
	s_ashr_i32 s17, s15, 7
	s_and_b32 s15, s15, 0x7ffff80
	s_sub_i32 s15, s13, s15
	s_lshl_b32 s16, s15, 5
	v_lshrrev_b32_e32 v41, 3, v38
	v_lshl_or_b32 v24, s17, 6, v41
	s_ashr_i32 s17, s16, 31
	s_lshl_b64 s[16:17], s[16:17], 2
	s_waitcnt lgkmcnt(0)
	s_add_u32 s16, s6, s16
	s_addc_u32 s17, s7, s17
	v_and_b32_e32 v34, 0x70, v39
	v_mov_b32_e32 v35, 0
	v_ashrrev_i32_e32 v25, 31, v24
	v_lshl_add_u64 v[26:27], s[16:17], 0, v[34:35]
	v_lshlrev_b64 v[0:1], 14, v[24:25]
	v_lshl_add_u64 v[8:9], v[26:27], 0, v[0:1]
	v_or_b32_e32 v0, 8, v24
	v_ashrrev_i32_e32 v1, 31, v0
	v_lshlrev_b64 v[0:1], 14, v[0:1]
	v_lshl_add_u64 v[10:11], v[26:27], 0, v[0:1]
	global_load_dwordx4 v[0:3], v[8:9], off nt
	global_load_dwordx4 v[4:7], v[10:11], off nt
	v_or_b32_e32 v8, 16, v24
	v_ashrrev_i32_e32 v9, 31, v8
	v_lshlrev_b64 v[8:9], 14, v[8:9]
	v_lshl_add_u64 v[16:17], v[26:27], 0, v[8:9]
	v_or_b32_e32 v8, 24, v24
	v_ashrrev_i32_e32 v9, 31, v8
	v_lshlrev_b64 v[8:9], 14, v[8:9]
	v_lshl_add_u64 v[18:19], v[26:27], 0, v[8:9]
	global_load_dwordx4 v[8:11], v[16:17], off nt
	global_load_dwordx4 v[12:15], v[18:19], off nt
	v_or_b32_e32 v16, 32, v24
	v_ashrrev_i32_e32 v17, 31, v16
	v_lshlrev_b64 v[16:17], 14, v[16:17]
	v_lshl_add_u64 v[28:29], v[26:27], 0, v[16:17]
	v_or_b32_e32 v16, 40, v24
	v_ashrrev_i32_e32 v17, 31, v16
	v_lshlrev_b64 v[16:17], 14, v[16:17]
	v_lshl_add_u64 v[30:31], v[26:27], 0, v[16:17]
	global_load_dwordx4 v[16:19], v[28:29], off nt
	global_load_dwordx4 v[20:23], v[30:31], off nt
	v_or_b32_e32 v28, 48, v24
	v_ashrrev_i32_e32 v29, 31, v28
	v_or_b32_e32 v24, 56, v24
	v_lshlrev_b64 v[28:29], 14, v[28:29]
	v_ashrrev_i32_e32 v25, 31, v24
	v_lshl_add_u64 v[32:33], v[26:27], 0, v[28:29]
	v_lshlrev_b64 v[24:25], 14, v[24:25]
	v_lshl_add_u64 v[42:43], v[26:27], 0, v[24:25]
	global_load_dwordx4 v[24:27], v[32:33], off nt
	global_load_dwordx4 v[28:31], v[42:43], off nt
	v_add_u32_e32 v43, s8, v34
	v_lshl_add_u64 v[32:33], s[6:7], 0, v[34:35]
	v_and_b32_e32 v34, 56, v37
	v_mul_u32_u24_e32 v42, 0x84, v34
	v_lshlrev_b32_e32 v34, 1, v34
	v_mul_u32_u24_e32 v44, 0x84, v41
	v_lshl_add_u64 v[34:35], s[4:5], 0, v[34:35]
	s_mov_b64 s[6:7], 0xb00000
	v_lshlrev_b32_e32 v45, 2, v41
	s_lshl_b32 s16, s10, 5
	v_lshl_add_u64 v[34:35], v[34:35], 0, s[6:7]
	v_add3_u32 v42, s8, v42, v45
	s_lshl_b32 s15, s13, 5
	v_add_u32_e32 v43, v43, v44
	s_mov_b32 s17, s16
	v_mov_b32_e32 v44, v41
	s_branch .LBB0_27

; #define INP(k) input_ptr(args, (k))
; __global__ void __launch_bounds__(NTHR, 2) fwd(Args args) {
;     ...
;             const int nitems = 64 * 16;
;             for (int it = ((gw - base) % NGW + NGW) % NGW; it < nitems; it += NGW) { const int sb = it >> 4, kb = (it >> 2) & 3, nb = it & 3;
;                 const int half = sb & 1, blk = (sb >> 1) & 7, g = (sb >> 4) & 1, dir = sb >> 5;
;                 const float* src = INP(I_LGW) + (size_t)(((dir * 2 + g) * 8 + blk)) * 65536 + half * 128;
;                 bf16_t* dst = (bf16_t*)(ws + W_LRU_G) + ((size_t)(((dir * 8 + blk) * 2 + half) * 256 + g * 128)) * 256;
;                 tr_item(src, 256, dst, 256, 64 * kb, 32 * nb, scr, lane); }
.LBB0_29:
	s_add_i32 s6, s11, 0xfffff000
	s_ashr_i32 s7, s6, 31
	s_abs_i32 s6, s6
	s_mul_hi_u32 s13, s6, s12
	s_mul_i32 s13, s13, s9
	s_sub_i32 s6, s6, s13
	s_sub_i32 s13, s6, s9
	s_cmp_ge_u32 s6, s9
	s_cselect_b32 s6, s13, s6
	s_sub_i32 s13, s6, s9
	s_cmp_ge_u32 s6, s9
	s_cselect_b32 s6, s13, s6
	s_xor_b32 s6, s6, s7
	s_sub_i32 s6, s6, s7
	s_add_i32 s6, s6, s10
	s_ashr_i32 s17, s6, 31
	s_abs_i32 s6, s6
	s_mul_hi_u32 s7, s6, s12
	s_mul_i32 s7, s7, s9
	s_sub_i32 s6, s6, s7
	s_sub_i32 s7, s6, s9
	s_cmp_ge_u32 s6, s9
	s_cselect_b32 s6, s7, s6
	s_sub_i32 s7, s6, s9
	s_cmp_ge_u32 s6, s9
	s_cselect_b32 s6, s7, s6
	s_xor_b32 s18, s6, s17
	s_sub_i32 s6, s18, s17
	s_cmpk_gt_i32 s6, 0x3ff
	s_cbranch_scc1 .LBB0_32
	v_readlane_b32 s98, v255, 63
	s_nop 0
	s_cmp_eq_u32 s98, 1
	s_cbranch_scc1 .LBB0_32
	s_waitcnt vmcnt(10)
	v_lshrrev_b32_e32 v6, 3, v38
	v_and_b32_e32 v0, 28, v40
	s_add_u32 s7, s4, 0x1b00000
	v_lshl_add_u32 v5, v0, 2, s8
	s_waitcnt vmcnt(9)
	v_mul_u32_u24_e32 v11, 0x84, v6
	v_and_b32_e32 v4, 56, v37
	s_addc_u32 s13, s5, 0
	v_mov_b32_e32 v1, 0
	v_mul_u32_u24_e32 v2, 0x84, v4
	v_lshlrev_b32_e32 v3, 2, v6
	s_lshl_b32 s15, s18, 4
	s_lshl_b32 s16, s17, 4
	s_lshl_b32 s18, s18, 5
	s_lshl_b32 s17, s17, 5
	v_add_u32_e32 v11, v5, v11
	v_add3_u32 v7, s8, v2, v3
	v_or_b32_e32 v8, 8, v6
	v_or_b32_e32 v9, 16, v6
	v_or_b32_e32 v10, 24, v6
	s_sub_i32 s15, s15, s16
	s_lshl_b32 s16, s14, 7
	s_sub_i32 s17, s18, s17
	s_lshl_b32 s14, s14, 8
	v_lshlrev_b32_e32 v2, 2, v0
	v_mov_b32_e32 v3, v1
	s_movk_i32 s18, 0x2000
	s_movk_i32 s19, 0x4000
	s_movk_i32 s21, 0x6000
	s_mov_b32 s22, 0x8000
	s_mov_b32 s23, 0xa000
	s_mov_b32 s24, 0xc000
	s_mov_b32 s25, 0xe000
	s_waitcnt vmcnt(8)
	v_add_u32_e32 v12, 0x420, v11
	v_add_u32_e32 v13, 0x428, v11
	v_add_u32_e32 v14, 0x840, v11
	v_add_u32_e32 v15, 0x848, v11
	s_waitcnt vmcnt(7)
	v_add_u32_e32 v16, 0xc60, v11
	v_add_u32_e32 v17, 0xc68, v11
	v_add_u32_e32 v18, 0x1080, v11
	v_add_u32_e32 v19, 0x1088, v11
	s_waitcnt vmcnt(6)
	v_add_u32_e32 v20, 0x14a0, v11
	v_add_u32_e32 v21, 0x14a8, v11
	v_add_u32_e32 v22, 0x18c0, v11
	v_add_u32_e32 v23, 0x18c8, v11
	s_waitcnt vmcnt(5)
	v_add_u32_e32 v24, 0x1ce0, v11
	v_add_u32_e32 v25, 0x1ce8, v11
	v_lshlrev_b32_e32 v4, 1, v4
	v_mov_b32_e32 v5, v1

; #define LAS __attribute__((address_space(3)))
; __device__ __forceinline__ unsigned pk2(float lo, float hi) { return cvt_pk_bf16(lo, hi); }
; __device__ __forceinline__ void tr_load(const float* W, int ldw, int k0, int n0, int lane, f32x4 (&v)[8]) {
; #pragma unroll
;     for (int i = 0; i < 8; ++i) v[i] = __builtin_nontemporal_load((const f32x4*)(W + (size_t)(k0 + 8 * i + (lane >> 3)) * ldw + n0 + 4 * (lane & 7)));
; }
; __device__ __forceinline__ void tr_put(LAS float* scr, int lane, const f32x4 (&v)[8]) {
; #pragma unroll
;     for (int i = 0; i < 8; ++i) { LAS float* p = scr + (8 * i + (lane >> 3)) * 33 + 4 * (lane & 7); p[0] = v[i][0]; p[1] = v[i][1]; p[2] = v[i][2]; p[3] = v[i][3]; }
;     asm volatile("s_waitcnt lgkmcnt(0)" ::: "memory");
; }
; __device__ __forceinline__ void tr_out(bf16_t* WT, int ldt, int k0, int n0, const LAS float* scr, int lane) {
;     const int c = lane & 7;
; #pragma unroll
;     for (int j = 0; j < 4; ++j) { const int n = (lane >> 3) + 8 * j; const LAS float* s = scr + (8 * c) * 33 + n;
;         u32x4 o; o.x = pk2(s[0 * 33], s[1 * 33]); o.y = pk2(s[2 * 33], s[3 * 33]); o.z = pk2(s[4 * 33], s[5 * 33]); o.w = pk2(s[6 * 33], s[7 * 33]);
;         *(u32x4*)(WT + (size_t)(n0 + n) * ldt + k0 + 8 * c) = o; }
;     asm volatile("s_waitcnt lgkmcnt(0)" ::: "memory");
; }
; __device__ __forceinline__ void tr_item(const float* W, int ldw, bf16_t* WT, int ldt, int k0, int n0, LAS float* scr, int lane) {
;     f32x4 v[8]; tr_load(W, ldw, k0, n0, lane, v); tr_put(scr, lane, v); tr_out(WT, ldt, k0, n0, scr, lane);
; }
; __device__ __forceinline__ void tr_job(const float* W, int K, int N, bf16_t* WT, LAS float* scr, int lane, int gw, int NGW, int& base) {
;     const int nblk = N / 32, nitems = (K / 64) * nblk;
;     int it = ((gw - base) % NGW + NGW) % NGW; f32x4 v[8];
;     if (it < nitems) tr_load(W, N, 64 * (it / nblk), 32 * (it % nblk), lane, v);
; #pragma unroll 1
;     while (it < nitems) {
;         tr_put(scr, lane, v);
;         const int nit = it + NGW;
;         if (nit < nitems) tr_load(W, N, 64 * (nit / nblk), 32 * (nit % nblk), lane, v);
;         tr_out(WT, K, 64 * (it / nblk), 32 * (it % nblk), scr, lane);
;         it = nit;
;     }
;     base += nitems;
; }
; __global__ void __launch_bounds__(NTHR, 2) fwd(Args args) {
;     ...
;         tr_job(INP(I_LOUT), D, D, (bf16_t*)(ws + W_LRU_OUT), scr, lane, gw, NGW, base);
.LBB0_32:
	s_add_i32 s6, s11, 0xffffec00
	s_ashr_i32 s7, s6, 31
	s_abs_i32 s6, s6
	s_mul_hi_u32 s13, s6, s12
	s_mul_i32 s13, s13, s9
	s_sub_i32 s6, s6, s13
	s_sub_i32 s13, s6, s9
	s_cmp_ge_u32 s6, s9
	s_cselect_b32 s6, s13, s6
	s_sub_i32 s13, s6, s9
	s_cmp_ge_u32 s6, s9
	s_cselect_b32 s6, s13, s6
	s_xor_b32 s6, s6, s7
	s_sub_i32 s6, s6, s7
	s_add_i32 s6, s6, s10
	s_ashr_i32 s7, s6, 31
	s_abs_i32 s6, s6
	s_mul_hi_u32 s13, s6, s12
	s_mul_i32 s13, s13, s9
	s_sub_i32 s6, s6, s13
	s_sub_i32 s13, s6, s9
	s_cmp_ge_u32 s6, s9
	s_cselect_b32 s6, s13, s6
	s_sub_i32 s13, s6, s9
	s_cmp_ge_u32 s6, s9
	s_cselect_b32 s6, s13, s6
	s_xor_b32 s6, s6, s7
	s_waitcnt vmcnt(11)
	v_mov_b32_e32 v0, 16
	s_sub_i32 s13, s6, s7
	s_cmpk_gt_i32 s13, 0x7ff
	v_readfirstlane_b32 s6, v0
	s_cbranch_scc1 .LBB0_37
	v_readlane_b32 s98, v255, 63
	s_nop 0
	s_cmp_eq_u32 s98, 1
	s_cbranch_scc1 .LBB0_37
	s_ashr_i32 s7, s6, 31
	s_lshl_b64 s[6:7], s[6:7], 3
	s_add_u32 s6, s0, s6
	s_addc_u32 s7, s1, s7
	s_ashr_i32 s14, s13, 31
	s_lshr_b32 s14, s14, 26
	s_add_i32 s14, s13, s14
	s_load_dwordx2 s[6:7], s[6:7], 0x0
	s_and_b32 s15, s14, 0xffffffc0
	s_sub_i32 s14, s13, s15
	s_lshl_b32 s14, s14, 5
	v_lshrrev_b32_e32 v40, 3, v38
	s_waitcnt vmcnt(5)
	v_or_b32_e32 v24, s15, v40
	s_ashr_i32 s15, s14, 31
	s_lshl_b64 s[14:15], s[14:15], 2
	s_waitcnt lgkmcnt(0)
	s_add_u32 s14, s6, s14
	s_addc_u32 s15, s7, s15
	v_and_b32_e32 v34, 0x70, v39
	v_mov_b32_e32 v35, 0
	v_ashrrev_i32_e32 v25, 31, v24
	v_lshl_add_u64 v[26:27], s[14:15], 0, v[34:35]
	v_lshlrev_b64 v[0:1], 13, v[24:25]
	v_lshl_add_u64 v[8:9], v[26:27], 0, v[0:1]
	v_or_b32_e32 v0, 8, v24
	v_ashrrev_i32_e32 v1, 31, v0
	v_lshlrev_b64 v[0:1], 13, v[0:1]
	v_lshl_add_u64 v[10:11], v[26:27], 0, v[0:1]
	global_load_dwordx4 v[0:3], v[8:9], off nt
	global_load_dwordx4 v[4:7], v[10:11], off nt
	v_or_b32_e32 v8, 16, v24
	v_ashrrev_i32_e32 v9, 31, v8
	v_lshlrev_b64 v[8:9], 13, v[8:9]
	v_lshl_add_u64 v[16:17], v[26:27], 0, v[8:9]
	v_or_b32_e32 v8, 24, v24
	v_ashrrev_i32_e32 v9, 31, v8
	v_lshlrev_b64 v[8:9], 13, v[8:9]
	v_lshl_add_u64 v[18:19], v[26:27], 0, v[8:9]
	global_load_dwordx4 v[8:11], v[16:17], off nt
	global_load_dwordx4 v[12:15], v[18:19], off nt
	v_or_b32_e32 v16, 32, v24
	v_ashrrev_i32_e32 v17, 31, v16
	v_lshlrev_b64 v[16:17], 13, v[16:17]
	s_waitcnt vmcnt(8)
	v_lshl_add_u64 v[28:29], v[26:27], 0, v[16:17]
	v_or_b32_e32 v16, 40, v24
	v_ashrrev_i32_e32 v17, 31, v16
	v_lshlrev_b64 v[16:17], 13, v[16:17]
	v_lshl_add_u64 v[30:31], v[26:27], 0, v[16:17]
	global_load_dwordx4 v[16:19], v[28:29], off nt
	global_load_dwordx4 v[20:23], v[30:31], off nt
	v_or_b32_e32 v28, 48, v24
	v_ashrrev_i32_e32 v29, 31, v28
	v_or_b32_e32 v24, 56, v24
	v_lshlrev_b64 v[28:29], 13, v[28:29]
	v_ashrrev_i32_e32 v25, 31, v24
	v_lshl_add_u64 v[32:33], v[26:27], 0, v[28:29]
	v_lshlrev_b64 v[24:25], 13, v[24:25]
	v_lshl_add_u64 v[42:43], v[26:27], 0, v[24:25]
	global_load_dwordx4 v[24:27], v[32:33], off nt
	global_load_dwordx4 v[28:31], v[42:43], off nt
	v_add_u32_e32 v42, s8, v34
	v_lshl_add_u64 v[32:33], s[6:7], 0, v[34:35]
	v_and_b32_e32 v34, 56, v37
	v_mul_u32_u24_e32 v41, 0x84, v34
	v_lshlrev_b32_e32 v34, 1, v34
	v_mul_u32_u24_e32 v43, 0x84, v40
	v_lshl_add_u64 v[34:35], s[4:5], 0, v[34:35]
	s_mov_b64 s[6:7], 0x1f00000
	v_lshlrev_b32_e32 v44, 2, v40
	s_lshl_b32 s15, s10, 5
	v_lshl_add_u64 v[34:35], v[34:35], 0, s[6:7]
	v_add3_u32 v41, s8, v41, v44
	s_lshl_b32 s14, s13, 5
	v_add_u32_e32 v42, v42, v43
	s_mov_b32 s16, s15
	v_mov_b32_e32 v43, v40
	s_branch .LBB0_35

; #define LAS __attribute__((address_space(3)))
; __device__ __forceinline__ unsigned pk2(float lo, float hi) { return cvt_pk_bf16(lo, hi); }
; __device__ __forceinline__ void tr_load(const float* W, int ldw, int k0, int n0, int lane, f32x4 (&v)[8]) {
; #pragma unroll
;     for (int i = 0; i < 8; ++i) v[i] = __builtin_nontemporal_load((const f32x4*)(W + (size_t)(k0 + 8 * i + (lane >> 3)) * ldw + n0 + 4 * (lane & 7)));
; }
; __device__ __forceinline__ void tr_put(LAS float* scr, int lane, const f32x4 (&v)[8]) {
; #pragma unroll
;     for (int i = 0; i < 8; ++i) { LAS float* p = scr + (8 * i + (lane >> 3)) * 33 + 4 * (lane & 7); p[0] = v[i][0]; p[1] = v[i][1]; p[2] = v[i][2]; p[3] = v[i][3]; }
;     asm volatile("s_waitcnt lgkmcnt(0)" ::: "memory");
; }
; __device__ __forceinline__ void tr_out(bf16_t* WT, int ldt, int k0, int n0, const LAS float* scr, int lane) {
;     const int c = lane & 7;
; #pragma unroll
;     for (int j = 0; j < 4; ++j) { const int n = (lane >> 3) + 8 * j; const LAS float* s = scr + (8 * c) * 33 + n;
;         u32x4 o; o.x = pk2(s[0 * 33], s[1 * 33]); o.y = pk2(s[2 * 33], s[3 * 33]); o.z = pk2(s[4 * 33], s[5 * 33]); o.w = pk2(s[6 * 33], s[7 * 33]);
;         *(u32x4*)(WT + (size_t)(n0 + n) * ldt + k0 + 8 * c) = o; }
;     asm volatile("s_waitcnt lgkmcnt(0)" ::: "memory");
; }
; __device__ __forceinline__ void tr_item(const float* W, int ldw, bf16_t* WT, int ldt, int k0, int n0, LAS float* scr, int lane) {
;     f32x4 v[8]; tr_load(W, ldw, k0, n0, lane, v); tr_put(scr, lane, v); tr_out(WT, ldt, k0, n0, scr, lane);
; }
; __device__ __forceinline__ void tr_job(const float* W, int K, int N, bf16_t* WT, LAS float* scr, int lane, int gw, int NGW, int& base) {
;     const int nblk = N / 32, nitems = (K / 64) * nblk;
;     int it = ((gw - base) % NGW + NGW) % NGW; f32x4 v[8];
;     if (it < nitems) tr_load(W, N, 64 * (it / nblk), 32 * (it % nblk), lane, v);
; #pragma unroll 1
;     while (it < nitems) {
;         tr_put(scr, lane, v);
;         const int nit = it + NGW;
;         if (nit < nitems) tr_load(W, N, 64 * (nit / nblk), 32 * (nit % nblk), lane, v);
;         tr_out(WT, K, 64 * (it / nblk), 32 * (it % nblk), scr, lane);
;         it = nit;
;     }
;     base += nitems;
; }
; __global__ void __launch_bounds__(NTHR, 2) fwd(Args args) {
;     ...
;         tr_job(INP(I_DQKV), D, 6144, (bf16_t*)(ws + W_DIF_QKV), scr, lane, gw, NGW, base);
.LBB0_37:
	s_add_i32 s6, s11, 0xffffe400
	s_ashr_i32 s7, s6, 31
	s_abs_i32 s6, s6
	s_mul_hi_u32 s13, s6, s12
	s_mul_i32 s13, s13, s9
	s_sub_i32 s6, s6, s13
	s_sub_i32 s13, s6, s9
	s_cmp_ge_u32 s6, s9
	s_cselect_b32 s6, s13, s6
	s_sub_i32 s13, s6, s9
	s_cmp_ge_u32 s6, s9
	s_cselect_b32 s6, s13, s6
	s_xor_b32 s6, s6, s7
	s_sub_i32 s6, s6, s7
	s_add_i32 s6, s6, s10
	s_ashr_i32 s7, s6, 31
	s_abs_i32 s6, s6
	s_mul_hi_u32 s13, s6, s12
	s_mul_i32 s13, s13, s9
	s_sub_i32 s6, s6, s13
	s_sub_i32 s13, s6, s9
	s_cmp_ge_u32 s6, s9
	s_cselect_b32 s6, s13, s6
	s_sub_i32 s13, s6, s9
	s_cmp_ge_u32 s6, s9
	s_cselect_b32 s6, s13, s6
	s_xor_b32 s6, s6, s7
	s_waitcnt vmcnt(11)
	v_mov_b32_e32 v0, 17
	s_sub_i32 s17, s6, s7
	s_cmpk_gt_i32 s17, 0x17ff
	v_readfirstlane_b32 s6, v0
	s_cbranch_scc1 .LBB0_42
	v_readlane_b32 s98, v255, 63
	s_nop 0
	s_cmp_eq_u32 s98, 0
	s_cbranch_scc1 .LBB0_42
	s_ashr_i32 s7, s6, 31
	s_lshl_b64 s[6:7], s[6:7], 3
	s_add_u32 s6, s0, s6
	s_mul_hi_i32 s13, s17, 0x2aaaaaab
	s_addc_u32 s7, s1, s7
	s_lshr_b32 s14, s13, 31
	s_ashr_i32 s13, s13, 5
	s_add_i32 s13, s13, s14
	s_load_dwordx2 s[6:7], s[6:7], 0x0
	s_mul_i32 s14, s13, 0xc0
	s_sub_i32 s14, s17, s14
	s_lshl_b32 s14, s14, 5
	s_ashr_i32 s15, s14, 31
	s_lshl_b64 s[14:15], s[14:15], 2
	s_waitcnt lgkmcnt(0)
	s_add_u32 s14, s6, s14
	v_lshrrev_b32_e32 v40, 3, v38
	s_addc_u32 s15, s7, s15
	v_and_b32_e32 v34, 0x70, v39
	v_mov_b32_e32 v35, 0
	s_waitcnt vmcnt(4)
	v_lshl_or_b32 v30, s13, 6, v40
	v_lshl_add_u64 v[24:25], s[14:15], 0, v[34:35]
	s_movk_i32 s13, 0x6000
	v_mad_i64_i32 v[8:9], s[14:15], v30, s13, v[24:25]
	v_or_b32_e32 v0, 8, v30
	v_mad_i64_i32 v[10:11], s[14:15], v0, s13, v[24:25]
	global_load_dwordx4 v[0:3], v[8:9], off nt
	global_load_dwordx4 v[4:7], v[10:11], off nt
	v_or_b32_e32 v8, 16, v30
	v_mad_i64_i32 v[16:17], s[14:15], v8, s13, v[24:25]
	v_or_b32_e32 v8, 24, v30
	v_mad_i64_i32 v[18:19], s[14:15], v8, s13, v[24:25]
	global_load_dwordx4 v[8:11], v[16:17], off nt
	global_load_dwordx4 v[12:15], v[18:19], off nt
	v_or_b32_e32 v16, 32, v30
	v_mad_i64_i32 v[26:27], s[14:15], v16, s13, v[24:25]
	v_or_b32_e32 v16, 40, v30
	v_mad_i64_i32 v[28:29], s[14:15], v16, s13, v[24:25]
	global_load_dwordx4 v[16:19], v[26:27], off nt
	global_load_dwordx4 v[20:23], v[28:29], off nt
	v_or_b32_e32 v26, 48, v30
	v_mad_i64_i32 v[32:33], s[14:15], v26, s13, v[24:25]
	v_or_b32_e32 v26, 56, v30
	v_mad_i64_i32 v[42:43], s[14:15], v26, s13, v[24:25]
	global_load_dwordx4 v[24:27], v[32:33], off nt
	global_load_dwordx4 v[28:31], v[42:43], off nt
	v_add_u32_e32 v42, s8, v34
	v_lshl_add_u64 v[32:33], s[6:7], 0, v[34:35]
	v_and_b32_e32 v34, 56, v37
	v_mul_u32_u24_e32 v41, 0x84, v34
	v_lshlrev_b32_e32 v34, 1, v34
	v_mul_u32_u24_e32 v43, 0x84, v40
	v_lshl_add_u64 v[34:35], s[4:5], 0, v[34:35]
	s_mov_b64 s[6:7], 0x2700000
	v_lshlrev_b32_e32 v44, 2, v40
	s_lshl_b32 s15, s10, 5
	v_lshl_add_u64 v[34:35], v[34:35], 0, s[6:7]
	v_add3_u32 v41, s8, v41, v44
	s_lshl_b32 s14, s17, 5
	v_add_u32_e32 v42, v42, v43
	s_mov_b32 s16, s15
	v_mov_b32_e32 v43, v40
	s_branch .LBB0_40

; #define LAS __attribute__((address_space(3)))
; __device__ __forceinline__ unsigned pk2(float lo, float hi) { return cvt_pk_bf16(lo, hi); }
; __device__ __forceinline__ void tr_load(const float* W, int ldw, int k0, int n0, int lane, f32x4 (&v)[8]) {
; #pragma unroll
;     for (int i = 0; i < 8; ++i) v[i] = __builtin_nontemporal_load((const f32x4*)(W + (size_t)(k0 + 8 * i + (lane >> 3)) * ldw + n0 + 4 * (lane & 7)));
; }
; __device__ __forceinline__ void tr_put(LAS float* scr, int lane, const f32x4 (&v)[8]) {
; #pragma unroll
;     for (int i = 0; i < 8; ++i) { LAS float* p = scr + (8 * i + (lane >> 3)) * 33 + 4 * (lane & 7); p[0] = v[i][0]; p[1] = v[i][1]; p[2] = v[i][2]; p[3] = v[i][3]; }
;     asm volatile("s_waitcnt lgkmcnt(0)" ::: "memory");
; }
; __device__ __forceinline__ void tr_out(bf16_t* WT, int ldt, int k0, int n0, const LAS float* scr, int lane) {
;     const int c = lane & 7;
; #pragma unroll
;     for (int j = 0; j < 4; ++j) { const int n = (lane >> 3) + 8 * j; const LAS float* s = scr + (8 * c) * 33 + n;
;         u32x4 o; o.x = pk2(s[0 * 33], s[1 * 33]); o.y = pk2(s[2 * 33], s[3 * 33]); o.z = pk2(s[4 * 33], s[5 * 33]); o.w = pk2(s[6 * 33], s[7 * 33]);
;         *(u32x4*)(WT + (size_t)(n0 + n) * ldt + k0 + 8 * c) = o; }
;     asm volatile("s_waitcnt lgkmcnt(0)" ::: "memory");
; }
; __device__ __forceinline__ void tr_item(const float* W, int ldw, bf16_t* WT, int ldt, int k0, int n0, LAS float* scr, int lane) {
;     f32x4 v[8]; tr_load(W, ldw, k0, n0, lane, v); tr_put(scr, lane, v); tr_out(WT, ldt, k0, n0, scr, lane);
; }
; __device__ __forceinline__ void tr_job(const float* W, int K, int N, bf16_t* WT, LAS float* scr, int lane, int gw, int NGW, int& base) {
;     const int nblk = N / 32, nitems = (K / 64) * nblk;
;     int it = ((gw - base) % NGW + NGW) % NGW; f32x4 v[8];
;     if (it < nitems) tr_load(W, N, 64 * (it / nblk), 32 * (it % nblk), lane, v);
; #pragma unroll 1
;     while (it < nitems) {
;         tr_put(scr, lane, v);
;         const int nit = it + NGW;
;         if (nit < nitems) tr_load(W, N, 64 * (nit / nblk), 32 * (nit % nblk), lane, v);
;         tr_out(WT, K, 64 * (it / nblk), 32 * (it % nblk), scr, lane);
;         it = nit;
;     }
;     base += nitems;
; }
; __global__ void __launch_bounds__(NTHR, 2) fwd(Args args) {
;     ...
;         tr_job(INP(I_DOUT), D, D, (bf16_t*)(ws + W_DIF_OUT), scr, lane, gw, NGW, base);
.LBB0_42:
	s_add_i32 s6, s11, 0xffffcc00
	s_ashr_i32 s7, s6, 31
	s_abs_i32 s6, s6
	s_mul_hi_u32 s13, s6, s12
	s_mul_i32 s13, s13, s9
	s_sub_i32 s6, s6, s13
	s_sub_i32 s13, s6, s9
	s_cmp_ge_u32 s6, s9
	s_cselect_b32 s6, s13, s6
	s_sub_i32 s13, s6, s9
	s_cmp_ge_u32 s6, s9
	s_cselect_b32 s6, s13, s6
	s_xor_b32 s6, s6, s7
	s_sub_i32 s6, s6, s7
	s_add_i32 s6, s6, s10
	s_ashr_i32 s7, s6, 31
	s_abs_i32 s6, s6
	s_mul_hi_u32 s13, s6, s12
	s_mul_i32 s13, s13, s9
	s_sub_i32 s6, s6, s13
	s_sub_i32 s13, s6, s9
	s_cmp_ge_u32 s6, s9
	s_cselect_b32 s6, s13, s6
	s_sub_i32 s13, s6, s9
	s_cmp_ge_u32 s6, s9
	s_cselect_b32 s6, s13, s6
	s_xor_b32 s6, s6, s7
	s_waitcnt vmcnt(11)
	v_mov_b32_e32 v0, 20
	s_sub_i32 s13, s6, s7
	s_cmpk_gt_i32 s13, 0x7ff
	v_readfirstlane_b32 s6, v0
	s_cbranch_scc1 .LBB0_47
	v_readlane_b32 s98, v255, 63
	s_nop 0
	s_cmp_eq_u32 s98, 0
	s_cbranch_scc1 .LBB0_47
	s_ashr_i32 s7, s6, 31
	s_lshl_b64 s[6:7], s[6:7], 3
	s_add_u32 s6, s0, s6
	s_addc_u32 s7, s1, s7
	s_ashr_i32 s14, s13, 31
	s_lshr_b32 s14, s14, 26
	s_add_i32 s14, s13, s14
	s_load_dwordx2 s[6:7], s[6:7], 0x0
	s_and_b32 s15, s14, 0xffffffc0
	s_sub_i32 s14, s13, s15
	s_lshl_b32 s14, s14, 5
	v_lshrrev_b32_e32 v40, 3, v38
	s_waitcnt vmcnt(5)
	v_or_b32_e32 v24, s15, v40
	s_ashr_i32 s15, s14, 31
	s_lshl_b64 s[14:15], s[14:15], 2
	s_waitcnt lgkmcnt(0)
	s_add_u32 s14, s6, s14
	s_addc_u32 s15, s7, s15
	v_and_b32_e32 v34, 0x70, v39
	v_mov_b32_e32 v35, 0
	v_ashrrev_i32_e32 v25, 31, v24
	v_lshl_add_u64 v[26:27], s[14:15], 0, v[34:35]
	v_lshlrev_b64 v[0:1], 13, v[24:25]
	v_lshl_add_u64 v[8:9], v[26:27], 0, v[0:1]
	v_or_b32_e32 v0, 8, v24
	v_ashrrev_i32_e32 v1, 31, v0
	v_lshlrev_b64 v[0:1], 13, v[0:1]
	v_lshl_add_u64 v[10:11], v[26:27], 0, v[0:1]
	global_load_dwordx4 v[0:3], v[8:9], off nt
	global_load_dwordx4 v[4:7], v[10:11], off nt
	v_or_b32_e32 v8, 16, v24
	v_ashrrev_i32_e32 v9, 31, v8
	v_lshlrev_b64 v[8:9], 13, v[8:9]
	v_lshl_add_u64 v[16:17], v[26:27], 0, v[8:9]
	v_or_b32_e32 v8, 24, v24
	v_ashrrev_i32_e32 v9, 31, v8
	v_lshlrev_b64 v[8:9], 13, v[8:9]
	v_lshl_add_u64 v[18:19], v[26:27], 0, v[8:9]
	global_load_dwordx4 v[8:11], v[16:17], off nt
	global_load_dwordx4 v[12:15], v[18:19], off nt
	v_or_b32_e32 v16, 32, v24
	v_ashrrev_i32_e32 v17, 31, v16
	v_lshlrev_b64 v[16:17], 13, v[16:17]
	s_waitcnt vmcnt(8)
	v_lshl_add_u64 v[28:29], v[26:27], 0, v[16:17]
	v_or_b32_e32 v16, 40, v24
	v_ashrrev_i32_e32 v17, 31, v16
	v_lshlrev_b64 v[16:17], 13, v[16:17]
	v_lshl_add_u64 v[30:31], v[26:27], 0, v[16:17]
	global_load_dwordx4 v[16:19], v[28:29], off nt
	global_load_dwordx4 v[20:23], v[30:31], off nt
	v_or_b32_e32 v28, 48, v24
	v_ashrrev_i32_e32 v29, 31, v28
	v_or_b32_e32 v24, 56, v24
	v_lshlrev_b64 v[28:29], 13, v[28:29]
	v_ashrrev_i32_e32 v25, 31, v24
	v_lshl_add_u64 v[32:33], v[26:27], 0, v[28:29]
	v_lshlrev_b64 v[24:25], 13, v[24:25]
	v_lshl_add_u64 v[42:43], v[26:27], 0, v[24:25]
	global_load_dwordx4 v[24:27], v[32:33], off nt
	global_load_dwordx4 v[28:31], v[42:43], off nt
	v_add_u32_e32 v42, s8, v34
	v_lshl_add_u64 v[32:33], s[6:7], 0, v[34:35]
	v_and_b32_e32 v34, 56, v37
	v_mul_u32_u24_e32 v41, 0x84, v34
	v_lshlrev_b32_e32 v34, 1, v34
	v_mul_u32_u24_e32 v43, 0x84, v40
	v_lshl_add_u64 v[34:35], s[4:5], 0, v[34:35]
	s_mov_b64 s[6:7], 0x3f00000
	v_lshlrev_b32_e32 v44, 2, v40
	s_lshl_b32 s15, s10, 5
	v_lshl_add_u64 v[34:35], v[34:35], 0, s[6:7]
	v_add3_u32 v41, s8, v41, v44
	s_lshl_b32 s14, s13, 5
	v_add_u32_e32 v42, v42, v43
	s_mov_b32 s16, s15
	v_mov_b32_e32 v43, v40
	s_branch .LBB0_45

; #define LAS __attribute__((address_space(3)))
; __device__ __forceinline__ unsigned pk2(float lo, float hi) { return cvt_pk_bf16(lo, hi); }
; __device__ __forceinline__ void tr_load(const float* W, int ldw, int k0, int n0, int lane, f32x4 (&v)[8]) {
; #pragma unroll
;     for (int i = 0; i < 8; ++i) v[i] = __builtin_nontemporal_load((const f32x4*)(W + (size_t)(k0 + 8 * i + (lane >> 3)) * ldw + n0 + 4 * (lane & 7)));
; }
; __device__ __forceinline__ void tr_put(LAS float* scr, int lane, const f32x4 (&v)[8]) {
; #pragma unroll
;     for (int i = 0; i < 8; ++i) { LAS float* p = scr + (8 * i + (lane >> 3)) * 33 + 4 * (lane & 7); p[0] = v[i][0]; p[1] = v[i][1]; p[2] = v[i][2]; p[3] = v[i][3]; }
;     asm volatile("s_waitcnt lgkmcnt(0)" ::: "memory");
; }
; __device__ __forceinline__ void tr_out(bf16_t* WT, int ldt, int k0, int n0, const LAS float* scr, int lane) {
;     const int c = lane & 7;
; #pragma unroll
;     for (int j = 0; j < 4; ++j) { const int n = (lane >> 3) + 8 * j; const LAS float* s = scr + (8 * c) * 33 + n;
;         u32x4 o; o.x = pk2(s[0 * 33], s[1 * 33]); o.y = pk2(s[2 * 33], s[3 * 33]); o.z = pk2(s[4 * 33], s[5 * 33]); o.w = pk2(s[6 * 33], s[7 * 33]);
;         *(u32x4*)(WT + (size_t)(n0 + n) * ldt + k0 + 8 * c) = o; }
;     asm volatile("s_waitcnt lgkmcnt(0)" ::: "memory");
; }
; __device__ __forceinline__ void tr_item(const float* W, int ldw, bf16_t* WT, int ldt, int k0, int n0, LAS float* scr, int lane) {
;     f32x4 v[8]; tr_load(W, ldw, k0, n0, lane, v); tr_put(scr, lane, v); tr_out(WT, ldt, k0, n0, scr, lane);
; }
; __device__ __forceinline__ void tr_job(const float* W, int K, int N, bf16_t* WT, LAS float* scr, int lane, int gw, int NGW, int& base) {
;     const int nblk = N / 32, nitems = (K / 64) * nblk;
;     int it = ((gw - base) % NGW + NGW) % NGW; f32x4 v[8];
;     if (it < nitems) tr_load(W, N, 64 * (it / nblk), 32 * (it % nblk), lane, v);
; #pragma unroll 1
;     while (it < nitems) {
;         tr_put(scr, lane, v);
;         const int nit = it + NGW;
;         if (nit < nitems) tr_load(W, N, 64 * (nit / nblk), 32 * (nit % nblk), lane, v);
;         tr_out(WT, K, 64 * (it / nblk), 32 * (it % nblk), scr, lane);
;         it = nit;
;     }
;     base += nitems;
; }
; __global__ void __launch_bounds__(NTHR, 2) fwd(Args args) {
;     ...
;         tr_job(INP(I_RQKVG), D, 12288, (bf16_t*)(ws + W_RET_QKVG), scr, lane, gw, NGW, base);
.LBB0_47:
	s_add_i32 s6, s11, 0xffffc400
	s_ashr_i32 s7, s6, 31
	s_abs_i32 s6, s6
	s_mul_hi_u32 s13, s6, s12
	s_mul_i32 s13, s13, s9
	s_sub_i32 s6, s6, s13
	s_sub_i32 s13, s6, s9
	s_cmp_ge_u32 s6, s9
	s_cselect_b32 s6, s13, s6
	s_sub_i32 s13, s6, s9
	s_cmp_ge_u32 s6, s9
	s_cselect_b32 s6, s13, s6
	s_xor_b32 s6, s6, s7
	s_sub_i32 s6, s6, s7
	s_add_i32 s6, s6, s10
	s_ashr_i32 s7, s6, 31
	s_abs_i32 s6, s6
	s_mul_hi_u32 s13, s6, s12
	s_mul_i32 s13, s13, s9
	s_sub_i32 s6, s6, s13
	s_sub_i32 s13, s6, s9
	s_cmp_ge_u32 s6, s9
	s_cselect_b32 s6, s13, s6
	s_sub_i32 s13, s6, s9
	s_cmp_ge_u32 s6, s9
	s_cselect_b32 s6, s13, s6
	s_xor_b32 s6, s6, s7
	s_waitcnt vmcnt(11)
	v_mov_b32_e32 v0, 21
	s_sub_i32 s17, s6, s7
	s_cmpk_gt_i32 s17, 0x2fff
	v_readfirstlane_b32 s6, v0
	s_cbranch_scc1 .LBB0_52
	v_readlane_b32 s98, v255, 63
	s_nop 0
	s_cmp_eq_u32 s98, 0
	s_cbranch_scc1 .LBB0_52
	s_ashr_i32 s7, s6, 31
	s_lshl_b64 s[6:7], s[6:7], 3
	s_add_u32 s6, s0, s6
	s_mul_hi_i32 s13, s17, 0x2aaaaaab
	s_addc_u32 s7, s1, s7
	s_lshr_b32 s14, s13, 31
	s_ashr_i32 s13, s13, 6
	s_add_i32 s13, s13, s14
	s_load_dwordx2 s[6:7], s[6:7], 0x0
	s_mul_i32 s14, s13, 0x180
	s_sub_i32 s14, s17, s14
	s_lshl_b32 s14, s14, 5
	s_ashr_i32 s15, s14, 31
	s_lshl_b64 s[14:15], s[14:15], 2
	s_waitcnt lgkmcnt(0)
	s_add_u32 s14, s6, s14
	v_lshrrev_b32_e32 v40, 3, v38
	s_addc_u32 s15, s7, s15
	v_and_b32_e32 v34, 0x70, v39
	v_mov_b32_e32 v35, 0
	s_waitcnt vmcnt(4)
	v_lshl_or_b32 v30, s13, 6, v40
	v_lshl_add_u64 v[24:25], s[14:15], 0, v[34:35]
	s_mov_b32 s13, 0xc000
	v_mad_i64_i32 v[8:9], s[14:15], v30, s13, v[24:25]
	v_or_b32_e32 v0, 8, v30
	v_mad_i64_i32 v[10:11], s[14:15], v0, s13, v[24:25]
	global_load_dwordx4 v[0:3], v[8:9], off nt
	global_load_dwordx4 v[4:7], v[10:11], off nt
	v_or_b32_e32 v8, 16, v30
	v_mad_i64_i32 v[16:17], s[14:15], v8, s13, v[24:25]
	v_or_b32_e32 v8, 24, v30
	v_mad_i64_i32 v[18:19], s[14:15], v8, s13, v[24:25]
	global_load_dwordx4 v[8:11], v[16:17], off nt
	global_load_dwordx4 v[12:15], v[18:19], off nt
	v_or_b32_e32 v16, 32, v30
	v_mad_i64_i32 v[26:27], s[14:15], v16, s13, v[24:25]
	v_or_b32_e32 v16, 40, v30
	v_mad_i64_i32 v[28:29], s[14:15], v16, s13, v[24:25]
	global_load_dwordx4 v[16:19], v[26:27], off nt
	global_load_dwordx4 v[20:23], v[28:29], off nt
	v_or_b32_e32 v26, 48, v30
	v_mad_i64_i32 v[32:33], s[14:15], v26, s13, v[24:25]
	v_or_b32_e32 v26, 56, v30
	v_mad_i64_i32 v[42:43], s[14:15], v26, s13, v[24:25]
	global_load_dwordx4 v[24:27], v[32:33], off nt
	global_load_dwordx4 v[28:31], v[42:43], off nt
	v_add_u32_e32 v42, s8, v34
	v_lshl_add_u64 v[32:33], s[6:7], 0, v[34:35]
	v_and_b32_e32 v34, 56, v37
	v_mul_u32_u24_e32 v41, 0x84, v34
	v_lshlrev_b32_e32 v34, 1, v34
	v_mul_u32_u24_e32 v43, 0x84, v40
	v_lshl_add_u64 v[34:35], s[4:5], 0, v[34:35]
	s_mov_b64 s[6:7], 0x4700000
	v_lshlrev_b32_e32 v44, 2, v40
	s_lshl_b32 s15, s10, 5
	v_lshl_add_u64 v[34:35], v[34:35], 0, s[6:7]
	v_add3_u32 v41, s8, v41, v44
	s_lshl_b32 s14, s17, 5
	v_add_u32_e32 v42, v42, v43
	s_mov_b32 s16, s15
	v_mov_b32_e32 v43, v40
	s_branch .LBB0_50

; #define LAS __attribute__((address_space(3)))
; __device__ __forceinline__ unsigned pk2(float lo, float hi) { return cvt_pk_bf16(lo, hi); }
; __device__ __forceinline__ void tr_load(const float* W, int ldw, int k0, int n0, int lane, f32x4 (&v)[8]) {
; #pragma unroll
;     for (int i = 0; i < 8; ++i) v[i] = __builtin_nontemporal_load((const f32x4*)(W + (size_t)(k0 + 8 * i + (lane >> 3)) * ldw + n0 + 4 * (lane & 7)));
; }
; __device__ __forceinline__ void tr_put(LAS float* scr, int lane, const f32x4 (&v)[8]) {
; #pragma unroll
;     for (int i = 0; i < 8; ++i) { LAS float* p = scr + (8 * i + (lane >> 3)) * 33 + 4 * (lane & 7); p[0] = v[i][0]; p[1] = v[i][1]; p[2] = v[i][2]; p[3] = v[i][3]; }
;     asm volatile("s_waitcnt lgkmcnt(0)" ::: "memory");
; }
; __device__ __forceinline__ void tr_out(bf16_t* WT, int ldt, int k0, int n0, const LAS float* scr, int lane) {
;     const int c = lane & 7;
; #pragma unroll
;     for (int j = 0; j < 4; ++j) { const int n = (lane >> 3) + 8 * j; const LAS float* s = scr + (8 * c) * 33 + n;
;         u32x4 o; o.x = pk2(s[0 * 33], s[1 * 33]); o.y = pk2(s[2 * 33], s[3 * 33]); o.z = pk2(s[4 * 33], s[5 * 33]); o.w = pk2(s[6 * 33], s[7 * 33]);
;         *(u32x4*)(WT + (size_t)(n0 + n) * ldt + k0 + 8 * c) = o; }
;     asm volatile("s_waitcnt lgkmcnt(0)" ::: "memory");
; }
; __device__ __forceinline__ void tr_item(const float* W, int ldw, bf16_t* WT, int ldt, int k0, int n0, LAS float* scr, int lane) {
;     f32x4 v[8]; tr_load(W, ldw, k0, n0, lane, v); tr_put(scr, lane, v); tr_out(WT, ldt, k0, n0, scr, lane);
; }
; __device__ __forceinline__ void tr_job(const float* W, int K, int N, bf16_t* WT, LAS float* scr, int lane, int gw, int NGW, int& base) {
;     const int nblk = N / 32, nitems = (K / 64) * nblk;
;     int it = ((gw - base) % NGW + NGW) % NGW; f32x4 v[8];
;     if (it < nitems) tr_load(W, N, 64 * (it / nblk), 32 * (it % nblk), lane, v);
; #pragma unroll 1
;     while (it < nitems) {
;         tr_put(scr, lane, v);
;         const int nit = it + NGW;
;         if (nit < nitems) tr_load(W, N, 64 * (nit / nblk), 32 * (nit % nblk), lane, v);
;         tr_out(WT, K, 64 * (it / nblk), 32 * (it % nblk), scr, lane);
;         it = nit;
;     }
;     base += nitems;
; }
; __global__ void __launch_bounds__(NTHR, 2) fwd(Args args) {
;     ...
;         tr_job(INP(I_SOUT), D, D, (bf16_t*)(ws + W_SWA_OUT), scr, lane, gw, NGW, base);
.LBB0_52:
	s_add_i32 s6, s11, 0xffff9400
	s_ashr_i32 s7, s6, 31
	s_abs_i32 s6, s6
	s_mul_hi_u32 s13, s6, s12
	s_mul_i32 s13, s13, s9
	s_sub_i32 s6, s6, s13
	s_sub_i32 s13, s6, s9
	s_cmp_ge_u32 s6, s9
	s_cselect_b32 s6, s13, s6
	s_sub_i32 s13, s6, s9
	s_cmp_ge_u32 s6, s9
	s_cselect_b32 s6, s13, s6
	s_xor_b32 s6, s6, s7
	s_sub_i32 s6, s6, s7
	s_add_i32 s6, s6, s10
	s_ashr_i32 s7, s6, 31
	s_abs_i32 s6, s6
	s_mul_hi_u32 s13, s6, s12
	s_mul_i32 s13, s13, s9
	s_sub_i32 s6, s6, s13
	s_sub_i32 s13, s6, s9
	s_cmp_ge_u32 s6, s9
	s_cselect_b32 s6, s13, s6
	s_sub_i32 s13, s6, s9
	s_cmp_ge_u32 s6, s9
	s_cselect_b32 s6, s13, s6
	s_xor_b32 s6, s6, s7
	s_waitcnt vmcnt(11)
	v_mov_b32_e32 v0, 25
	s_sub_i32 s13, s6, s7
	s_cmpk_gt_i32 s13, 0x7ff
	v_readfirstlane_b32 s6, v0
	s_cbranch_scc1 .LBB0_57
	v_readlane_b32 s98, v255, 63
	s_nop 0
	s_cmp_eq_u32 s98, 0
	s_cbranch_scc1 .LBB0_57
	s_ashr_i32 s7, s6, 31
	s_lshl_b64 s[6:7], s[6:7], 3
	s_add_u32 s6, s0, s6
	s_addc_u32 s7, s1, s7
	s_ashr_i32 s14, s13, 31
	s_lshr_b32 s14, s14, 26
	s_add_i32 s14, s13, s14
	s_load_dwordx2 s[6:7], s[6:7], 0x0
	s_and_b32 s15, s14, 0xffffffc0
	s_sub_i32 s14, s13, s15
	s_lshl_b32 s14, s14, 5
	v_lshrrev_b32_e32 v40, 3, v38
	s_waitcnt vmcnt(5)
	v_or_b32_e32 v24, s15, v40
	s_ashr_i32 s15, s14, 31
	s_lshl_b64 s[14:15], s[14:15], 2
	s_waitcnt lgkmcnt(0)
	s_add_u32 s14, s6, s14
	s_addc_u32 s15, s7, s15
	v_and_b32_e32 v34, 0x70, v39
	v_mov_b32_e32 v35, 0
	v_ashrrev_i32_e32 v25, 31, v24
	v_lshl_add_u64 v[26:27], s[14:15], 0, v[34:35]
	v_lshlrev_b64 v[0:1], 13, v[24:25]
	v_lshl_add_u64 v[8:9], v[26:27], 0, v[0:1]
	v_or_b32_e32 v0, 8, v24
	v_ashrrev_i32_e32 v1, 31, v0
	v_lshlrev_b64 v[0:1], 13, v[0:1]
	v_lshl_add_u64 v[10:11], v[26:27], 0, v[0:1]
	global_load_dwordx4 v[0:3], v[8:9], off nt
	global_load_dwordx4 v[4:7], v[10:11], off nt
	v_or_b32_e32 v8, 16, v24
	v_ashrrev_i32_e32 v9, 31, v8
	v_lshlrev_b64 v[8:9], 13, v[8:9]
	v_lshl_add_u64 v[16:17], v[26:27], 0, v[8:9]
	v_or_b32_e32 v8, 24, v24
	v_ashrrev_i32_e32 v9, 31, v8
	v_lshlrev_b64 v[8:9], 13, v[8:9]
	v_lshl_add_u64 v[18:19], v[26:27], 0, v[8:9]
	global_load_dwordx4 v[8:11], v[16:17], off nt
	global_load_dwordx4 v[12:15], v[18:19], off nt
	v_or_b32_e32 v16, 32, v24
	v_ashrrev_i32_e32 v17, 31, v16
	v_lshlrev_b64 v[16:17], 13, v[16:17]
	s_waitcnt vmcnt(8)
	v_lshl_add_u64 v[28:29], v[26:27], 0, v[16:17]
	v_or_b32_e32 v16, 40, v24
	v_ashrrev_i32_e32 v17, 31, v16
	v_lshlrev_b64 v[16:17], 13, v[16:17]
	v_lshl_add_u64 v[30:31], v[26:27], 0, v[16:17]
	global_load_dwordx4 v[16:19], v[28:29], off nt
	global_load_dwordx4 v[20:23], v[30:31], off nt
	v_or_b32_e32 v28, 48, v24
	v_ashrrev_i32_e32 v29, 31, v28
	v_or_b32_e32 v24, 56, v24
	v_lshlrev_b64 v[28:29], 13, v[28:29]
	v_ashrrev_i32_e32 v25, 31, v24
	v_lshl_add_u64 v[32:33], v[26:27], 0, v[28:29]
	v_lshlrev_b64 v[24:25], 13, v[24:25]
	v_lshl_add_u64 v[42:43], v[26:27], 0, v[24:25]
	global_load_dwordx4 v[24:27], v[32:33], off nt
	global_load_dwordx4 v[28:31], v[42:43], off nt
	v_add_u32_e32 v42, s8, v34
	v_lshl_add_u64 v[32:33], s[6:7], 0, v[34:35]
	v_and_b32_e32 v34, 56, v37
	v_mul_u32_u24_e32 v41, 0x84, v34
	v_lshlrev_b32_e32 v34, 1, v34
	v_mul_u32_u24_e32 v43, 0x84, v40
	v_lshl_add_u64 v[34:35], s[4:5], 0, v[34:35]
	s_mov_b64 s[6:7], 0x9300000
	v_lshlrev_b32_e32 v44, 2, v40
	s_lshl_b32 s15, s10, 5
	v_lshl_add_u64 v[34:35], v[34:35], 0, s[6:7]
	v_add3_u32 v41, s8, v41, v44
	s_lshl_b32 s14, s13, 5
	v_add_u32_e32 v42, v42, v43
	s_mov_b32 s16, s15
	v_mov_b32_e32 v43, v40
	s_branch .LBB0_55

; #define LAS __attribute__((address_space(3)))
; __device__ __forceinline__ unsigned pk2(float lo, float hi) { return cvt_pk_bf16(lo, hi); }
; __device__ __forceinline__ void tr_load(const float* W, int ldw, int k0, int n0, int lane, f32x4 (&v)[8]) {
; #pragma unroll
;     for (int i = 0; i < 8; ++i) v[i] = __builtin_nontemporal_load((const f32x4*)(W + (size_t)(k0 + 8 * i + (lane >> 3)) * ldw + n0 + 4 * (lane & 7)));
; }
; __device__ __forceinline__ void tr_put(LAS float* scr, int lane, const f32x4 (&v)[8]) {
; #pragma unroll
;     for (int i = 0; i < 8; ++i) { LAS float* p = scr + (8 * i + (lane >> 3)) * 33 + 4 * (lane & 7); p[0] = v[i][0]; p[1] = v[i][1]; p[2] = v[i][2]; p[3] = v[i][3]; }
;     asm volatile("s_waitcnt lgkmcnt(0)" ::: "memory");
; }
; __device__ __forceinline__ void tr_out(bf16_t* WT, int ldt, int k0, int n0, const LAS float* scr, int lane) {
;     const int c = lane & 7;
; #pragma unroll
;     for (int j = 0; j < 4; ++j) { const int n = (lane >> 3) + 8 * j; const LAS float* s = scr + (8 * c) * 33 + n;
;         u32x4 o; o.x = pk2(s[0 * 33], s[1 * 33]); o.y = pk2(s[2 * 33], s[3 * 33]); o.z = pk2(s[4 * 33], s[5 * 33]); o.w = pk2(s[6 * 33], s[7 * 33]);
;         *(u32x4*)(WT + (size_t)(n0 + n) * ldt + k0 + 8 * c) = o; }
;     asm volatile("s_waitcnt lgkmcnt(0)" ::: "memory");
; }
; __device__ __forceinline__ void tr_item(const float* W, int ldw, bf16_t* WT, int ldt, int k0, int n0, LAS float* scr, int lane) {
;     f32x4 v[8]; tr_load(W, ldw, k0, n0, lane, v); tr_put(scr, lane, v); tr_out(WT, ldt, k0, n0, scr, lane);
; }
; __device__ __forceinline__ void tr_job(const float* W, int K, int N, bf16_t* WT, LAS float* scr, int lane, int gw, int NGW, int& base) {
;     const int nblk = N / 32, nitems = (K / 64) * nblk;
;     int it = ((gw - base) % NGW + NGW) % NGW; f32x4 v[8];
;     if (it < nitems) tr_load(W, N, 64 * (it / nblk), 32 * (it % nblk), lane, v);
; #pragma unroll 1
;     while (it < nitems) {
;         tr_put(scr, lane, v);
;         const int nit = it + NGW;
;         if (nit < nitems) tr_load(W, N, 64 * (nit / nblk), 32 * (nit % nblk), lane, v);
;         tr_out(WT, K, 64 * (it / nblk), 32 * (it % nblk), scr, lane);
;         it = nit;
;     }
;     base += nitems;
; }
; __global__ void __launch_bounds__(NTHR, 2) fwd(Args args) {
;     ...
;         tr_job(INP(I_W1), D, FF, (bf16_t*)(ws + W_MLP1), scr, lane, gw, NGW, base);
.LBB0_57:
	s_add_i32 s6, s11, 0xffff8c00
	s_ashr_i32 s7, s6, 31
	s_abs_i32 s6, s6
	s_mul_hi_u32 s13, s6, s12
	s_mul_i32 s13, s13, s9
	s_sub_i32 s6, s6, s13
	s_sub_i32 s13, s6, s9
	s_cmp_ge_u32 s6, s9
	s_cselect_b32 s6, s13, s6
	s_sub_i32 s13, s6, s9
	s_cmp_ge_u32 s6, s9
	s_cselect_b32 s6, s13, s6
	s_xor_b32 s6, s6, s7
	s_sub_i32 s6, s6, s7
	s_add_i32 s6, s6, s10
	s_ashr_i32 s7, s6, 31
	s_abs_i32 s6, s6
	s_mul_hi_u32 s13, s6, s12
	s_mul_i32 s13, s13, s9
	s_sub_i32 s6, s6, s13
	s_sub_i32 s13, s6, s9
	s_cmp_ge_u32 s6, s9
	s_cselect_b32 s6, s13, s6
	s_sub_i32 s13, s6, s9
	s_cmp_ge_u32 s6, s9
	s_cselect_b32 s6, s13, s6
	s_xor_b32 s6, s6, s7
	s_waitcnt vmcnt(11)
	v_mov_b32_e32 v0, 8
	s_sub_i32 s13, s6, s7
	s_cmpk_gt_i32 s13, 0x1fff
	v_readfirstlane_b32 s6, v0
	s_cbranch_scc1 .LBB0_62
	v_readlane_b32 s98, v255, 63
	s_nop 0
	s_cmp_eq_u32 s98, 1
	s_cbranch_scc1 .LBB0_62
	s_ashr_i32 s7, s6, 31
	s_lshl_b64 s[6:7], s[6:7], 3
	s_add_u32 s6, s0, s6
	s_addc_u32 s7, s1, s7
	s_ashr_i32 s14, s13, 31
	s_lshr_b32 s14, s14, 24
	s_add_i32 s14, s13, s14
	s_load_dwordx2 s[6:7], s[6:7], 0x0
	s_ashr_i32 s15, s14, 8
	s_and_b32 s14, s14, 0x7ffff00
	s_sub_i32 s14, s13, s14
	s_lshl_b32 s14, s14, 5
	v_lshrrev_b32_e32 v38, 3, v38
	s_waitcnt vmcnt(5)
	v_lshl_or_b32 v24, s15, 6, v38
	s_ashr_i32 s15, s14, 31
	s_lshl_b64 s[14:15], s[14:15], 2
	s_waitcnt lgkmcnt(0)
	s_add_u32 s14, s6, s14
	s_addc_u32 s15, s7, s15
	v_and_b32_e32 v34, 0x70, v39
	v_mov_b32_e32 v35, 0
	v_ashrrev_i32_e32 v25, 31, v24
	v_lshl_add_u64 v[26:27], s[14:15], 0, v[34:35]
	v_lshlrev_b64 v[0:1], 15, v[24:25]
	v_lshl_add_u64 v[8:9], v[26:27], 0, v[0:1]
	v_or_b32_e32 v0, 8, v24
	v_ashrrev_i32_e32 v1, 31, v0
	v_lshlrev_b64 v[0:1], 15, v[0:1]
	v_lshl_add_u64 v[10:11], v[26:27], 0, v[0:1]
	global_load_dwordx4 v[0:3], v[8:9], off nt
	global_load_dwordx4 v[4:7], v[10:11], off nt
	v_or_b32_e32 v8, 16, v24
	v_ashrrev_i32_e32 v9, 31, v8
	v_lshlrev_b64 v[8:9], 15, v[8:9]
	v_lshl_add_u64 v[16:17], v[26:27], 0, v[8:9]
	v_or_b32_e32 v8, 24, v24
	v_ashrrev_i32_e32 v9, 31, v8
	v_lshlrev_b64 v[8:9], 15, v[8:9]
	v_lshl_add_u64 v[18:19], v[26:27], 0, v[8:9]
	global_load_dwordx4 v[8:11], v[16:17], off nt
	global_load_dwordx4 v[12:15], v[18:19], off nt
	v_or_b32_e32 v16, 32, v24
	v_ashrrev_i32_e32 v17, 31, v16
	v_lshlrev_b64 v[16:17], 15, v[16:17]
	s_waitcnt vmcnt(8)
	v_lshl_add_u64 v[28:29], v[26:27], 0, v[16:17]
	v_or_b32_e32 v16, 40, v24
	v_ashrrev_i32_e32 v17, 31, v16
	v_lshlrev_b64 v[16:17], 15, v[16:17]
	v_lshl_add_u64 v[30:31], v[26:27], 0, v[16:17]
	global_load_dwordx4 v[16:19], v[28:29], off nt
	global_load_dwordx4 v[20:23], v[30:31], off nt
	v_or_b32_e32 v28, 48, v24
	v_ashrrev_i32_e32 v29, 31, v28
	v_or_b32_e32 v24, 56, v24
	v_lshlrev_b64 v[28:29], 15, v[28:29]
	v_ashrrev_i32_e32 v25, 31, v24
	v_lshl_add_u64 v[32:33], v[26:27], 0, v[28:29]
	v_lshlrev_b64 v[24:25], 15, v[24:25]
	v_lshl_add_u64 v[40:41], v[26:27], 0, v[24:25]
	global_load_dwordx4 v[24:27], v[32:33], off nt
	global_load_dwordx4 v[28:31], v[40:41], off nt
	v_add_u32_e32 v41, s8, v34
	v_lshl_add_u64 v[32:33], s[6:7], 0, v[34:35]
	v_and_b32_e32 v34, 56, v37
	v_mul_u32_u24_e32 v40, 0x84, v34
	v_lshlrev_b32_e32 v34, 1, v34
	v_mul_u32_u24_e32 v42, 0x84, v38
	v_lshl_add_u64 v[34:35], s[4:5], 0, v[34:35]
	s_mov_b64 s[6:7], 0x9b00000
	v_lshlrev_b32_e32 v43, 2, v38
	s_lshl_b32 s15, s10, 5
	v_lshl_add_u64 v[34:35], v[34:35], 0, s[6:7]
	v_add3_u32 v40, s8, v40, v43
	s_lshl_b32 s14, s13, 5
	v_add_u32_e32 v41, v41, v42
	s_mov_b32 s16, s15
	v_mov_b32_e32 v42, v38
	s_branch .LBB0_60

; #define LAS __attribute__((address_space(3)))
; __device__ __forceinline__ unsigned pk2(float lo, float hi) { return cvt_pk_bf16(lo, hi); }
; __device__ __forceinline__ void tr_load(const float* W, int ldw, int k0, int n0, int lane, f32x4 (&v)[8]) {
; #pragma unroll
;     for (int i = 0; i < 8; ++i) v[i] = __builtin_nontemporal_load((const f32x4*)(W + (size_t)(k0 + 8 * i + (lane >> 3)) * ldw + n0 + 4 * (lane & 7)));
; }
; __device__ __forceinline__ void tr_put(LAS float* scr, int lane, const f32x4 (&v)[8]) {
; #pragma unroll
;     for (int i = 0; i < 8; ++i) { LAS float* p = scr + (8 * i + (lane >> 3)) * 33 + 4 * (lane & 7); p[0] = v[i][0]; p[1] = v[i][1]; p[2] = v[i][2]; p[3] = v[i][3]; }
;     asm volatile("s_waitcnt lgkmcnt(0)" ::: "memory");
; }
; __device__ __forceinline__ void tr_out(bf16_t* WT, int ldt, int k0, int n0, const LAS float* scr, int lane) {
;     const int c = lane & 7;
; #pragma unroll
;     for (int j = 0; j < 4; ++j) { const int n = (lane >> 3) + 8 * j; const LAS float* s = scr + (8 * c) * 33 + n;
;         u32x4 o; o.x = pk2(s[0 * 33], s[1 * 33]); o.y = pk2(s[2 * 33], s[3 * 33]); o.z = pk2(s[4 * 33], s[5 * 33]); o.w = pk2(s[6 * 33], s[7 * 33]);
;         *(u32x4*)(WT + (size_t)(n0 + n) * ldt + k0 + 8 * c) = o; }
;     asm volatile("s_waitcnt lgkmcnt(0)" ::: "memory");
; }
; __device__ __forceinline__ void tr_item(const float* W, int ldw, bf16_t* WT, int ldt, int k0, int n0, LAS float* scr, int lane) {
;     f32x4 v[8]; tr_load(W, ldw, k0, n0, lane, v); tr_put(scr, lane, v); tr_out(WT, ldt, k0, n0, scr, lane);
; }
; __device__ __forceinline__ void tr_job(const float* W, int K, int N, bf16_t* WT, LAS float* scr, int lane, int gw, int NGW, int& base) {
;     const int nblk = N / 32, nitems = (K / 64) * nblk;
;     int it = ((gw - base) % NGW + NGW) % NGW; f32x4 v[8];
;     if (it < nitems) tr_load(W, N, 64 * (it / nblk), 32 * (it % nblk), lane, v);
; #pragma unroll 1
;     while (it < nitems) {
;         tr_put(scr, lane, v);
;         const int nit = it + NGW;
;         if (nit < nitems) tr_load(W, N, 64 * (nit / nblk), 32 * (nit % nblk), lane, v);
;         tr_out(WT, K, 64 * (it / nblk), 32 * (it % nblk), scr, lane);
;         it = nit;
;     }
;     base += nitems;
; }
; __global__ void __launch_bounds__(NTHR, 2) fwd(Args args) {
;     ...
;         tr_job(INP(I_W2), FF, D, (bf16_t*)(ws + W_MLP2), scr, lane, gw, NGW, base);
.LBB0_62:
	s_add_i32 s11, s11, 0xffff6c00
	s_abs_i32 s7, s11
	s_ashr_i32 s6, s11, 31
	s_mul_hi_u32 s11, s7, s12
	s_mul_i32 s11, s11, s9
	s_sub_i32 s7, s7, s11
	s_sub_i32 s11, s7, s9
	s_cmp_ge_u32 s7, s9
	s_cselect_b32 s7, s11, s7
	s_sub_i32 s11, s7, s9
	s_cmp_ge_u32 s7, s9
	s_cselect_b32 s7, s11, s7
	s_xor_b32 s7, s7, s6
	s_sub_i32 s6, s7, s6
	s_add_i32 s6, s6, s10
	s_ashr_i32 s7, s6, 31
	s_abs_i32 s6, s6
	s_mul_hi_u32 s11, s6, s12
	s_mul_i32 s11, s11, s9
	s_sub_i32 s6, s6, s11
	s_sub_i32 s11, s6, s9
	s_cmp_ge_u32 s6, s9
	s_cselect_b32 s6, s11, s6
	s_sub_i32 s11, s6, s9
	s_cmp_ge_u32 s6, s9
	s_cselect_b32 s6, s11, s6
	s_xor_b32 s6, s6, s7
	s_waitcnt vmcnt(11)
	v_mov_b32_e32 v0, 9
	s_sub_i32 s9, s6, s7
	s_cmpk_gt_i32 s9, 0x1fff
	v_readfirstlane_b32 s6, v0
	s_cbranch_scc1 .LBB0_67
	v_readlane_b32 s98, v255, 63
	s_nop 0
	s_cmp_eq_u32 s98, 1
	s_cbranch_scc1 .LBB0_67
	s_ashr_i32 s7, s6, 31
	s_lshl_b64 s[6:7], s[6:7], 3
	s_add_u32 s6, s0, s6
	s_addc_u32 s7, s1, s7
	s_ashr_i32 s11, s9, 31
	s_lshr_b32 s11, s11, 26
	s_add_i32 s11, s9, s11
	s_load_dwordx2 s[6:7], s[6:7], 0x0
	s_andn2_b32 s11, s11, 63
	s_sub_i32 s12, s9, s11
	s_lshl_b32 s12, s12, 5
	s_ashr_i32 s13, s12, 31
	s_lshl_b64 s[12:13], s[12:13], 2
	s_waitcnt vmcnt(5)
	v_or_b32_e32 v24, s11, v36
	s_waitcnt lgkmcnt(0)
	s_add_u32 s12, s6, s12
	s_addc_u32 s13, s7, s13
	v_and_b32_e32 v34, 0x70, v39
	v_mov_b32_e32 v35, 0
	v_ashrrev_i32_e32 v25, 31, v24
	v_lshl_add_u64 v[26:27], s[12:13], 0, v[34:35]
	v_lshlrev_b64 v[0:1], 13, v[24:25]
	v_lshl_add_u64 v[8:9], v[26:27], 0, v[0:1]
	v_or_b32_e32 v0, 8, v24
	v_ashrrev_i32_e32 v1, 31, v0
	v_lshlrev_b64 v[0:1], 13, v[0:1]
	v_lshl_add_u64 v[10:11], v[26:27], 0, v[0:1]
	global_load_dwordx4 v[0:3], v[8:9], off nt
	global_load_dwordx4 v[4:7], v[10:11], off nt
	v_or_b32_e32 v8, 16, v24
	v_ashrrev_i32_e32 v9, 31, v8
	v_lshlrev_b64 v[8:9], 13, v[8:9]
	v_lshl_add_u64 v[16:17], v[26:27], 0, v[8:9]
	v_or_b32_e32 v8, 24, v24
	v_ashrrev_i32_e32 v9, 31, v8
	v_lshlrev_b64 v[8:9], 13, v[8:9]
	v_lshl_add_u64 v[18:19], v[26:27], 0, v[8:9]
	global_load_dwordx4 v[8:11], v[16:17], off nt
	global_load_dwordx4 v[12:15], v[18:19], off nt
	v_or_b32_e32 v16, 32, v24
	v_ashrrev_i32_e32 v17, 31, v16
	v_lshlrev_b64 v[16:17], 13, v[16:17]
	s_waitcnt vmcnt(8)
	v_lshl_add_u64 v[28:29], v[26:27], 0, v[16:17]
	v_or_b32_e32 v16, 40, v24
	v_ashrrev_i32_e32 v17, 31, v16
	v_lshlrev_b64 v[16:17], 13, v[16:17]
	v_lshl_add_u64 v[30:31], v[26:27], 0, v[16:17]
	global_load_dwordx4 v[16:19], v[28:29], off nt
	global_load_dwordx4 v[20:23], v[30:31], off nt
	v_or_b32_e32 v28, 48, v24
	v_ashrrev_i32_e32 v29, 31, v28
	v_or_b32_e32 v24, 56, v24
	v_lshlrev_b64 v[28:29], 13, v[28:29]
	v_ashrrev_i32_e32 v25, 31, v24
	v_lshl_add_u64 v[32:33], v[26:27], 0, v[28:29]
	v_lshlrev_b64 v[24:25], 13, v[24:25]
	v_lshl_add_u64 v[38:39], v[26:27], 0, v[24:25]
	global_load_dwordx4 v[24:27], v[32:33], off nt
	global_load_dwordx4 v[28:31], v[38:39], off nt
	v_add_u32_e32 v38, s8, v34
	v_lshl_add_u64 v[32:33], s[6:7], 0, v[34:35]
	v_and_b32_e32 v34, 56, v37
	v_mul_u32_u24_e32 v37, 0x84, v34
	v_lshlrev_b32_e32 v34, 1, v34
	v_mul_u32_u24_e32 v39, 0x84, v36
	v_lshl_add_u64 v[34:35], s[4:5], 0, v[34:35]
	s_mov_b64 s[4:5], 0x11b00000
	v_lshlrev_b32_e32 v40, 2, v36
	s_lshl_b32 s7, s10, 5
	v_lshl_add_u64 v[34:35], v[34:35], 0, s[4:5]
	v_add3_u32 v37, s8, v37, v40
	s_lshl_b32 s6, s9, 5
	v_add_u32_e32 v38, v38, v39
	s_mov_b32 s8, s7
	v_mov_b32_e32 v39, v36
	s_branch .LBB0_65

; __device__ __forceinline__ unsigned xb_add(unsigned* p, unsigned v) { return __hip_atomic_fetch_add(p, v, __ATOMIC_RELAXED, __HIP_MEMORY_SCOPE_AGENT); }
; __device__ __forceinline__ void xcd_barrier(const XcdBarrier& b, const bool leader  ) {
;     asm volatile("s_waitcnt vmcnt(0)" ::: "memory");
;     __syncthreads();
;     if (leader) {
;         unsigned* bar = b.bar;
;         __builtin_amdgcn_s_waitcnt(0);
;         unsigned nloc = b.st[0], nx = b.st[1];
;         if (nloc == 0u) { xcd_barrier_complete(bar, b.x, nloc, nx); b.st[0] = nloc; b.st[1] = nx; }
;         const unsigned old = xb_add(&bar[XB_XSUB(b.x)], 1u);
;         const unsigned gen = old / nloc;
;         if (old + 1u == (gen + 1u) * nloc) {
;             __builtin_amdgcn_fence(__ATOMIC_RELEASE, "agent");
;             asm volatile("s_waitcnt vmcnt(0)" ::: "memory");
;             const unsigned og = xb_add(&bar[XB_TOP], 1u);
;             const unsigned tg = og / nx;
; __global__ void __launch_bounds__(NTHR, 2) fwd(Args args) {
;     ...
;         __syncthreads();
;         } SEAM(0);
.LBB0_67:
	v_readlane_b32 s98, v255, 63
	s_nop 0
	s_cmp_eq_u32 s98, 1
	s_cbranch_scc1 .Ltramp_back
	s_cmp_gt_i32 s91, 1
	s_barrier
	s_cbranch_scc0 .LBB0_121
	s_waitcnt vmcnt(11)
	v_mov_b32_e32 v0, 27
	s_getreg_b32 s10, hwreg(HW_REG_XCC_ID, 0, 4)
	v_readfirstlane_b32 s6, v0
	v_mbcnt_lo_u32_b32 v0, -1, 0
	v_mbcnt_hi_u32_b32 v0, -1, v0
	s_cmp_lt_u32 s85, 64
	s_waitcnt vmcnt(0)
	s_cselect_b64 s[4:5], -1, 0
	v_cmp_eq_u32_e32 vcc, 0, v0
	s_and_b64 s[8:9], s[4:5], vcc
	s_barrier
	s_and_saveexec_b64 s[4:5], s[8:9]
	s_cbranch_execz .LBB0_120
	s_ashr_i32 s7, s6, 31
	s_lshl_b64 s[6:7], s[6:7], 3
	s_add_u32 s6, s0, s6
	s_addc_u32 s7, s1, s7
	s_load_dwordx2 s[8:9], s[6:7], 0x0
	s_and_b32 s21, s10, 15
	s_waitcnt vmcnt(0) expcnt(0) lgkmcnt(0)
	s_add_u32 s6, s8, 0x4200
	s_addc_u32 s7, s9, 0
	s_add_i32 s10, 0, 0x23fa0
	v_mov_b32_e32 v0, s10
	ds_read_b32 v2, v0
	s_add_i32 s10, 0, 0x23fa4
	v_mov_b32_e32 v0, s10
	ds_read_b32 v0, v0
	s_waitcnt lgkmcnt(1)
	v_cmp_ne_u32_e32 vcc, 0, v2
	s_cbranch_vccnz .LBB0_84
	s_add_u32 s10, s8, 0x4400
	s_addc_u32 s11, s9, 0
	s_add_u32 s12, s8, 0x4500
	s_addc_u32 s13, s9, 0
	s_add_u32 s14, s8, 0x4600
	s_addc_u32 s15, s9, 0
	s_add_u32 s16, s8, 0x4700
	s_addc_u32 s17, s9, 0
	s_add_u32 s18, s8, 0x4800
	s_addc_u32 s19, s9, 0
	s_add_u32 s24, s8, 0x4900
	s_addc_u32 s25, s9, 0
	s_add_u32 s26, s8, 0x4a00
	s_addc_u32 s27, s9, 0
	s_add_u32 s28, s8, 0x4b00
	s_addc_u32 s29, s9, 0
	s_add_u32 s30, s8, 0x4c00
	s_addc_u32 s31, s9, 0
	s_add_u32 s34, s8, 0x4d00
	s_addc_u32 s35, s9, 0
	s_add_u32 s36, s8, 0x4e00
	s_addc_u32 s37, s9, 0
	s_add_u32 s38, s8, 0x4f00
	s_addc_u32 s39, s9, 0
	s_add_u32 s40, s8, 0x5000
	s_addc_u32 s41, s9, 0
	s_load_dwordx2 s[22:23], s[2:3], 0x4
	s_add_u32 s42, s8, 0x5100
	s_addc_u32 s43, s9, 0
	s_add_u32 s2, s8, 0x5200
	s_addc_u32 s3, s9, 0
	s_add_u32 s44, s8, 0x5300
	s_waitcnt lgkmcnt(0)
	s_mul_i32 s20, s22, s20
	s_addc_u32 s45, s9, 0
	s_mul_i32 s20, s20, s23
	s_mov_b32 s22, 1
	v_mov_b32_e32 v16, 0
	s_branch .LBB0_72

; #define PG8_WAIT_V(n) asm volatile("s_waitcnt vmcnt(" #n ")" ::: "memory")
; #define PG8_WAIT_L(n) asm volatile("s_waitcnt lgkmcnt(" #n ")" ::: "memory")
; #define PG8_BAR __builtin_amdgcn_s_barrier()
; template <class Epi, class Sched, bool ALIGN_EPI, bool LAST_FUSED = false, bool PERM = false, bool CARRY = false>
; __device__ __forceinline__ void gemm_phase(LAS unsigned char* lds, const int tid, const int K, const int lda, const int ldb, const Sched& S, const Epi& E) {
;     ...
;     for (;;) {
;         const bool has_next = S.next(KD_IDX(ui + 1), nxt);
;         const char* nA = has_next ? nxt.a : cA; const char* nB = has_next ? nxt.b : cB; const int nt = cur.nt;
; #pragma unroll 1
;         for (int t = 0; t < nt; t += 2) {
;             const bool last = (t == nt - 2);
;             const char* a1 = cA + (size_t)(t + 1) * kstep;
;             const char* a2 = last ? nA : cA + (size_t)(t + 2) * kstep; const char* b2 = last ? nB : cB + (size_t)(t + 2) * kstep;
;             const char* a3 = a2 + kstep; const char* b3 = b2 + kstep;
;             PG8_LDB(B0, 0, 0); PG8_LDB(B1, 0, 1); PG8_SCHED; PG8_LDA(At, 0, 0); PG8_STAGE(PG8_SA(1, 1), a1 + hstepA, voffA);
;             PG8_WAIT_V(8); PG8_WAIT_L(0); PG8_BAR; PG8_MMA(0, 0, At, B0); PG8_MMA(0, 1, At, B1); PG8_BAR; PG8_SCHED;
;             PG8_LDA(At, 0, 1); PG8_STAGE(PG8_SB(0, 0), b2, voffB); PG8_STAGE(PG8_SB(0, 1), b2 + hstepB, voffB); PG8_STAGE(PG8_SA(0, 0), a2, voffA);
;             PG8_WAIT_V(8); PG8_WAIT_L(0); PG8_BAR; PG8_MMA(1, 0, At, B0); PG8_MMA(1, 1, At, B1); PG8_BAR; PG8_SCHED;
;             PG8_LDB(B0, 1, 0); PG8_LDB(B1, 1, 1); PG8_SCHED; PG8_LDA(At, 1, 0); PG8_STAGE(PG8_SA(0, 1), a2 + hstepA, voffA);
;             PG8_WAIT_V(8); PG8_WAIT_L(0); PG8_BAR; PG8_MMA(0, 0, At, B0); PG8_MMA(0, 1, At, B1); PG8_BAR; PG8_SCHED;
;             PG8_LDA(At, 1, 1); PG8_STAGE(PG8_SB(1, 0), b3, voffB); PG8_STAGE(PG8_SB(1, 1), b3 + hstepB, voffB); PG8_STAGE(PG8_SA(1, 0), a3, voffA);
;             PG8_WAIT_V(8); PG8_WAIT_L(0); PG8_BAR; PG8_MMA(1, 0, At, B0); PG8_MMA(1, 1, At, B1); PG8_BAR; PG8_SCHED;
;         }
;         if constexpr (ALIGN_EPI) { if (wr == 0) PG8_BAR; }
;         if (KD_REAL(ui) && (!LAST_FUSED || has_next)) { int efr = fr, efq = fq, ewr = wr, ewc = wc; asm volatile("" : "+v"(efr), "+v"(efq), "+s"(ewr), "+s"(ewc));
;           E(acc, cur, ewr, ewc, efr, efq); }
;         if (!has_next) break;
.LBB0_525:
	s_andn2_b64 vcc, exec, s[2:3]
	s_mov_b64 s[2:3], -1
	s_cbranch_vccnz .LBB0_508
	s_branch .LBB0_528
.Ltramp_to_p0:
	s_branch .LBB0_24
.Ltramp_back:
	s_branch .Lsh_return
.LBB0_526:
	s_andn2_b64 vcc, exec, s[4:5]
	s_cbranch_vccnz .LBB0_525

; __device__ __forceinline__ unsigned xb_add(unsigned* p, unsigned v) { return __hip_atomic_fetch_add(p, v, __ATOMIC_RELAXED, __HIP_MEMORY_SCOPE_AGENT); }
; #define REPLOOP(k) _Pragma("unroll 1") for (int rep_ = 0, nrep_ = (phase_group(k) == DUP_GROUP ? 2 : 1); rep_ < nrep_; ++rep_)
; __device__ __forceinline__ void xcd_barrier(const XcdBarrier& b, const bool leader  ) {
;     asm volatile("s_waitcnt vmcnt(0)" ::: "memory");
;     __syncthreads();
;     if (leader) {
;         unsigned* bar = b.bar;
;         __builtin_amdgcn_s_waitcnt(0);
;         unsigned nloc = b.st[0], nx = b.st[1];
;         if (nloc == 0u) { xcd_barrier_complete(bar, b.x, nloc, nx); b.st[0] = nloc; b.st[1] = nx; }
;         const unsigned old = xb_add(&bar[XB_XSUB(b.x)], 1u);
;         const unsigned gen = old / nloc;
;         if (old + 1u == (gen + 1u) * nloc) {
;             __builtin_amdgcn_fence(__ATOMIC_RELEASE, "agent");
;             asm volatile("s_waitcnt vmcnt(0)" ::: "memory");
;             const unsigned og = xb_add(&bar[XB_TOP], 1u);
;             const unsigned tg = og / nx;
; __global__ void __launch_bounds__(NTHR, 2) fwd(Args args) {
;     ...
;             if (IN(Lb + 0)) { REPLOOP(Lb + 0) { PH_BEGIN(); ph_lru_in(lds, tid, ws, G, bid); } SEAM(Lb + 0); }
.LBB0_1212:
	s_waitcnt vmcnt(0)
	s_barrier
	v_readlane_b32 s98, v255, 36
	s_nop 0
	s_cmp_lt_u32 s98, 64
	s_cbranch_scc1 .Lsh_skip
	s_mov_b32 s99, 1
	v_writelane_b32 v255, s99, 63
	s_load_dwordx2 s[4:5], s[0:1], 0xd8
	v_readlane_b32 s12, v255, 37
	s_nop 0
	s_lshr_b32 s12, s12, 6
	s_sub_i32 s11, s98, 64
	s_lshl_b32 s11, s11, 3
	s_add_i32 s11, s11, s12
	s_movk_i32 s10, 0x600
	s_movk_i32 s14, 0x100
	v_mbcnt_lo_u32_b32 v38, -1, 0
	v_mbcnt_hi_u32_b32 v38, -1, v38
	v_and_b32_e32 v38, 63, v38
	v_lshlrev_b32_e32 v40, 2, v38
	s_waitcnt lgkmcnt(0)
	s_branch .Ltramp_to_p0
.Lsh_return:
	s_mov_b32 s99, 0
	v_writelane_b32 v255, s99, 63
	v_mov_b32_e32 v1, 0
	s_movk_i32 s21, 0x1000
	s_mov_b32 s25, 0
	s_mov_b32 s34, 0xbdcccccd
.Lsh_skip:
.LBB0_1213:
	v_readlane_b32 s2, v255, 12
	v_readlane_b32 s3, v255, 13
	s_andn2_b64 vcc, exec, s[2:3]
	s_cbranch_vccnz .LBB0_1267
	v_mov_b32_e32 v0, 27
	s_getreg_b32 s8, hwreg(HW_REG_XCC_ID, 0, 4)
	v_readfirstlane_b32 s4, v0
	v_mbcnt_lo_u32_b32 v0, -1, 0
	v_mbcnt_hi_u32_b32 v0, -1, v0
	v_readlane_b32 s2, v255, 0
	s_waitcnt vmcnt(0)
	v_cmp_eq_u32_e32 vcc, 0, v0
	v_readlane_b32 s3, v255, 1
	s_and_b64 s[6:7], s[2:3], vcc
	s_waitcnt vmcnt(0)
	s_barrier
	s_and_saveexec_b64 s[2:3], s[6:7]
	s_cbranch_execz .LBB0_1266
	s_ashr_i32 s5, s4, 31
	s_lshl_b64 s[4:5], s[4:5], 3
	s_add_u32 s4, s0, s4
	s_addc_u32 s5, s1, s5
	s_load_dwordx2 s[6:7], s[4:5], 0x0
	v_readlane_b32 s4, v255, 30
	s_waitcnt vmcnt(0) expcnt(0) lgkmcnt(0)
	v_readlane_b32 s5, v255, 31
	v_mov_b32_e32 v0, s4
	ds_read_b32 v3, v0
	v_mov_b32_e32 v0, s5
	ds_read_b32 v0, v0
	s_and_b32 s22, s8, 15
	s_add_u32 s4, s6, 0x4200
	s_waitcnt lgkmcnt(1)
	v_cmp_ne_u32_e32 vcc, 0, v3
	s_addc_u32 s5, s7, 0
	s_cbranch_vccnz .LBB0_1230
	s_add_u32 s8, s6, 0x4400
	s_addc_u32 s9, s7, 0
	s_add_u32 s10, s6, 0x4500
	s_addc_u32 s11, s7, 0
	s_add_u32 s12, s6, 0x4600
	s_addc_u32 s13, s7, 0
	s_add_u32 s14, s6, 0x4700
	s_addc_u32 s15, s7, 0
	s_add_u32 s16, s6, 0x4800
	s_addc_u32 s17, s7, 0
	s_add_u32 s18, s6, 0x4900
	s_addc_u32 s19, s7, 0
	s_add_u32 s26, s6, 0x4a00
	s_addc_u32 s27, s7, 0
	s_add_u32 s30, s6, 0x4b00
	s_addc_u32 s31, s7, 0
	s_add_u32 s36, s6, 0x4c00
	s_addc_u32 s37, s7, 0
	s_add_u32 s38, s6, 0x4d00
	s_addc_u32 s39, s7, 0
	s_add_u32 s40, s6, 0x4e00
	s_addc_u32 s41, s7, 0
	s_add_u32 s42, s6, 0x4f00
	s_addc_u32 s43, s7, 0
	s_add_u32 s46, s6, 0x5000
	s_addc_u32 s47, s7, 0
	s_load_dwordx2 s[28:29], s[86:87], 0x4
	s_add_u32 s48, s6, 0x5100
	s_addc_u32 s49, s7, 0
	s_add_u32 s50, s6, 0x5200
	s_addc_u32 s51, s7, 0
	s_add_u32 s52, s6, 0x5300
	s_waitcnt lgkmcnt(0)
	s_mul_i32 s20, s28, s20
	s_addc_u32 s53, s7, 0
	s_mul_i32 s20, s20, s29
	s_mov_b32 s23, 1
	s_branch .LBB0_1218
